# attention: unit remap so 16 WGs of an XCD sweep one (b,h) K/V in lockstep (ascending then descending tile order) for L2 reuse
# baseline (speedup 1.0000x reference)
; #define ATT_ISSUE(tilebase, bufbase) do { const unsigned char* _tb = (tilebase); asm volatile("" : "+s"(_tb)); _Pragma("unroll") for (int _i = 0; _i < 6; ++_i) { int _q = wave + 8 * _i; _q = _q > 44 ? 44 : _q; \
;         __builtin_amdgcn_global_load_lds((const unsigned*)(_tb + goff[_i]), (LAS unsigned*)((bufbase) + _q * 1024), 16, 0, 0); } } while (0)
; #define ATT_BAR() do { asm volatile("s_waitcnt vmcnt(0) lgkmcnt(0)" ::: "memory"); __builtin_amdgcn_s_barrier(); asm volatile("" ::: "memory"); } while (0)
; __device__ __forceinline__ void att_mfma(const Params& P, LAS unsigned char* lds, int wave) {
;     ...
;     for (int u = blockIdx.x; u < 1024; u += gridDim.x) {
;         const int bh = u & 63, r = u >> 6, kk = r >> 2, j4 = r & 3;
;         const int qb = kk == 0 ? j4 : (kk == 1 ? 15 - j4 : (kk == 2 ? 4 + j4 : 11 - j4));
;         const int b = bh >> 3, hh = bh & 7;
;         const int ntile = 4 * qb + 4, my_last = 4 * qb + w4;
;         const size_t qrow_g = (size_t)b * SEQ + qb * 256 + w4 * 64 + (wave >> 2) * 32 + q32;
;         const unsigned char* kvb = (const unsigned char*)(KV + (size_t)b * SEQ * 2560 + hh * 320);
;         ATT_ISSUE(kvb, lds);
;         bf16x8 qf[12];
;         { const bf16_t* qp = Q + qrow_g * 1536 + hh * 192 + hf * 8;
; #pragma unroll
;           for (int ks = 0; ks < 12; ++ks) qf[ks] = *(const bf16x8*)(qp + ks * 16); }
;         f32x16 o[4];
; #pragma unroll
;         for (int d = 0; d < 4; ++d)
; #pragma unroll
;             for (int i = 0; i < 16; ++i) o[d][i] = 0.f;
;         float mrun = -1e30f, lrun = 0.f;
;         bf16x8 pb[4];
; #pragma unroll
;         for (int i = 0; i < 4; ++i) pb[i] = (bf16x8){0, 0, 0, 0, 0, 0, 0, 0};
;         ATT_BAR();
; #pragma unroll
;         for (int ks = 0; ks < 12; ++ks) asm volatile("" : "+v"(qf[ks]));
;         {
;             float qv[12][8]; float sq = 0.f;
; #pragma unroll
;             for (int ks = 0; ks < 12; ++ks)
; #pragma unroll
;                 for (int e = 0; e < 8; ++e) { qv[ks][e] = bf2f((unsigned short)qf[ks][e]); sq += qv[ks][e] * qv[ks][e]; }
.LBB0_1008:
	s_lshr_b32 s79, s39, 8
	s_and_b32 s74, s39, 7
	s_lshl_b32 s74, s74, 3
	s_lshl_b32 s80, s79, 1
	s_add_i32 s74, s74, s80
	s_bfe_u32 s80, s39, 0x10007
	s_add_i32 s74, s74, s80
	s_and_b32 s74, s74, 63
	s_bfe_u32 s4, s39, 0x40003
	s_and_b32 s80, s79, 2
	s_lshl_b32 s80, s80, 2
	s_add_i32 s4, s4, s80
	s_and_b32 s4, s4, 15
	s_and_b32 s75, s79, 1
	s_mul_i32 s80, s75, 15
	s_xor_b32 s4, s4, s80
	s_lshr_b32 s5, s74, 3
	s_and_b32 s6, s74, 7
	s_mul_i32 s5, s5, 0x1400000
	s_mulk_i32 s6, 0x280
	s_or_b32 s5, s5, s6
	s_lshl_b32 s51, s4, 2
	s_add_i32 s50, s51, 4
	s_add_i32 s80, s50, -3
	s_mul_i32 s80, s80, s75
	s_mul_i32 s80, s80, 0x50000
	s_add_i32 s5, s5, s80
	s_add_u32 s10, s25, s5
	s_addc_u32 s11, s26, 0
	s_mov_b32 s77, 0x50000
	s_cmp_eq_u32 s75, 0
	s_cselect_b32 s77, s77, 0xfffb0000
	s_cselect_b32 s78, 0, -1
	s_lshl_b32 s5, s74, 9
	s_and_b32 s6, s5, 0x7000
	s_and_b32 s47, s74, 7
	s_lshl_b32 s16, s4, 8
	s_mul_i32 s4, s6, 0x1400
	s_add_u32 s4, s48, s4
	s_addc_u32 s5, s49, 0
	s_mul_i32 s17, s47, 0x280
	s_add_u32 s4, s4, s17
	s_addc_u32 s5, s5, 0
	s_add_i32 s80, s50, -1
	s_mul_i32 s80, s80, s75
	s_mul_i32 s80, s80, 0x50000
	s_add_u32 s4, s4, s80
	s_addc_u32 s5, s5, 0
	s_mov_b32 m0, s27
	s_add_i32 s16, s16, s6
	v_lshl_add_u64 v[0:1], s[4:5], 0, v[144:145]
	global_load_lds_dwordx4 v[0:1], off
	v_lshl_add_u64 v[0:1], s[4:5], 0, v[146:147]
	s_mov_b32 m0, s28
	v_add_u32_e32 v164, s16, v224
	global_load_lds_dwordx4 v[0:1], off
	v_lshl_add_u64 v[0:1], s[4:5], 0, v[148:149]
	s_mov_b32 m0, s29
	s_mul_i32 s6, s47, 0x180
	global_load_lds_dwordx4 v[0:1], off
	v_lshl_add_u64 v[0:1], s[4:5], 0, v[150:151]
	s_mov_b32 m0, s30
	s_mov_b32 s17, 2
	global_load_lds_dwordx4 v[0:1], off
	v_lshl_add_u64 v[0:1], s[4:5], 0, v[156:157]
	s_mov_b32 m0, s31
	s_mov_b32 s61, 1
	global_load_lds_dwordx4 v[0:1], off
	v_lshl_add_u64 v[0:1], s[4:5], 0, v[154:155]
	s_mov_b32 m0, s34
	s_mov_b32 s16, 0
	global_load_lds_dwordx4 v[0:1], off
	v_mad_u64_u32 v[0:1], s[4:5], v164, s35, v[166:167]
	v_lshl_add_u64 v[0:1], v[0:1], 0, s[6:7]
	v_lshl_add_u64 v[0:1], v[158:159], 1, v[0:1]
	flat_load_dwordx4 v[104:107], v[0:1]
	flat_load_dwordx4 v[108:111], v[0:1] offset:32
	flat_load_dwordx4 v[112:115], v[0:1] offset:64
	flat_load_dwordx4 v[116:119], v[0:1] offset:96
	flat_load_dwordx4 v[208:211], v[0:1] offset:128
	flat_load_dwordx4 v[200:203], v[0:1] offset:160
	flat_load_dwordx4 v[192:195], v[0:1] offset:192
	flat_load_dwordx4 v[184:187], v[0:1] offset:224
	flat_load_dwordx4 v[174:177], v[0:1] offset:256
	flat_load_dwordx4 v[132:135], v[0:1] offset:288
	flat_load_dwordx4 v[178:181], v[0:1] offset:320
	flat_load_dwordx4 v[138:141], v[0:1] offset:352
	s_waitcnt vmcnt(0) lgkmcnt(0)
	s_barrier
	v_lshlrev_b32_e32 v0, 7, v164
	v_mov_b32_e32 v1, v165
	v_and_b32_e32 v0, 0x7ff80, v0
	v_lshl_add_u64 v[142:143], v[162:163], 0, v[0:1]
	v_add_co_u32_e32 v246, vcc, s36, v142
	s_or_b32 s6, s51, s18
	s_nop 0
	v_addc_co_u32_e32 v247, vcc, 0, v143, vcc
	s_sub_i32 s76, 3, s18
	s_mul_i32 s76, s76, s75
	s_cmp_eq_u32 s75, 1
	s_cselect_b32 s6, 0xffff, s6
	s_add_i32 s51, s6, 1
	s_cmp_eq_u32 s18, 3
	s_cselect_b32 s80, 1, 0
	s_or_b32 s80, s80, s75
	s_cmp_lg_u32 s80, 0
	s_cselect_b64 s[8:9], -1, 0
	s_and_b64 s[8:9], s[0:1], s[8:9]
	s_mov_b32 s58, 0
	s_waitcnt vmcnt(0) lgkmcnt(0)
	s_nop 0
	v_and_b32_e32 v235, 0xffff0000, v104
	v_lshlrev_b32_e32 v234, 16, v104
	v_mul_f32_e32 v104, v235, v235
	v_and_b32_e32 v243, 0xffff0000, v105
	v_lshlrev_b32_e32 v242, 16, v105
	v_pk_fma_f32 v[104:105], v[234:235], v[234:235], v[104:105] op_sel_hi:[1,1,0]
	v_and_b32_e32 v233, 0xffff0000, v106
	v_lshlrev_b32_e32 v232, 16, v106
	v_pk_fma_f32 v[104:105], v[242:243], v[242:243], v[104:105]
	v_mul_f32_e32 v106, v243, v243
	v_pk_add_f32 v[104:105], v[106:107], v[104:105] op_sel_hi:[0,1]
	v_pk_fma_f32 v[104:105], v[232:233], v[232:233], v[104:105]
	v_mul_f32_e32 v106, v233, v233
	v_and_b32_e32 v241, 0xffff0000, v107
	v_lshlrev_b32_e32 v240, 16, v107
	v_pk_add_f32 v[104:105], v[106:107], v[104:105] op_sel_hi:[0,1]
	v_pk_fma_f32 v[104:105], v[240:241], v[240:241], v[104:105]
	v_mul_f32_e32 v106, v241, v241
	v_and_b32_e32 v219, 0xffff0000, v111
	v_lshlrev_b32_e32 v218, 16, v111
	v_and_b32_e32 v221, 0xffff0000, v110
	v_lshlrev_b32_e32 v220, 16, v110
	v_and_b32_e32 v111, 0xffff0000, v109
	v_lshlrev_b32_e32 v110, 16, v109
	v_and_b32_e32 v109, 0xffff0000, v108
	v_lshlrev_b32_e32 v108, 16, v108
	v_pk_add_f32 v[104:105], v[106:107], v[104:105] op_sel_hi:[0,1]
	v_pk_fma_f32 v[104:105], v[108:109], v[108:109], v[104:105]
	v_mul_f32_e32 v106, v109, v109
	v_pk_add_f32 v[104:105], v[106:107], v[104:105] op_sel_hi:[0,1]
	v_pk_fma_f32 v[104:105], v[110:111], v[110:111], v[104:105]
	v_mul_f32_e32 v106, v111, v111
	v_pk_add_f32 v[104:105], v[106:107], v[104:105] op_sel_hi:[0,1]
	v_pk_fma_f32 v[104:105], v[220:221], v[220:221], v[104:105]
	v_mul_f32_e32 v106, v221, v221
	v_pk_add_f32 v[104:105], v[106:107], v[104:105] op_sel_hi:[0,1]
	v_pk_fma_f32 v[104:105], v[218:219], v[218:219], v[104:105]
	v_mul_f32_e32 v106, v219, v219
	v_and_b32_e32 v215, 0xffff0000, v115
	v_lshlrev_b32_e32 v214, 16, v115
	v_and_b32_e32 v217, 0xffff0000, v114
	v_lshlrev_b32_e32 v216, 16, v114
	v_and_b32_e32 v115, 0xffff0000, v113
	v_lshlrev_b32_e32 v114, 16, v113
	v_and_b32_e32 v113, 0xffff0000, v112
	v_lshlrev_b32_e32 v112, 16, v112
	v_pk_add_f32 v[104:105], v[106:107], v[104:105] op_sel_hi:[0,1]
	v_pk_fma_f32 v[104:105], v[112:113], v[112:113], v[104:105]
	v_mul_f32_e32 v106, v113, v113
	v_pk_add_f32 v[104:105], v[106:107], v[104:105] op_sel_hi:[0,1]
	v_pk_fma_f32 v[104:105], v[114:115], v[114:115], v[104:105]
	v_mul_f32_e32 v106, v115, v115
	v_pk_add_f32 v[104:105], v[106:107], v[104:105] op_sel_hi:[0,1]
; __device__ __forceinline__ void att_mfma(const Params& P, LAS unsigned char* lds, int wave) {
;     ...
;             float qv[12][8]; float sq = 0.f;
; #pragma unroll
;             for (int ks = 0; ks < 12; ++ks)
; #pragma unroll
;                 for (int e = 0; e < 8; ++e) { qv[ks][e] = bf2f((unsigned short)qf[ks][e]); sq += qv[ks][e] * qv[ks][e]; }
;             { const auto rr = __builtin_amdgcn_permlane32_swap(__float_as_uint(sq), __float_as_uint(sq), false, false);
;               sq = __uint_as_float(rr[0]) + __uint_as_float(rr[1]); }
;             const float rs = __builtin_amdgcn_rsqf(sq * (1.f / 192.f) + EPS) * (0.07216878364870322f * 1.4426950408889634f);
;             const float* qg = (const float*)(ws + WS_SMALL) + 2048 + 8 * hf;
;             const int spos = (int)(qrow_g & (SEQ - 1));
;             const float* cM = (const float*)(ws + WS_ROPE_M) + spos * 32 + 8 * hf; const float* sM = cM + 4096 * 32;
; #pragma unroll
;             for (int ks = 0; ks < 12; ++ks) { const f32x4 g0 = *(const f32x4*)(qg + 16 * ks), g1 = *(const f32x4*)(qg + 16 * ks + 4);
	v_pk_fma_f32 v[104:105], v[216:217], v[216:217], v[104:105]
	v_mul_f32_e32 v106, v217, v217
	v_pk_add_f32 v[104:105], v[106:107], v[104:105] op_sel_hi:[0,1]
	v_pk_fma_f32 v[104:105], v[214:215], v[214:215], v[104:105]
	v_mul_f32_e32 v106, v215, v215
	v_and_b32_e32 v131, 0xffff0000, v133
	v_lshlrev_b32_e32 v130, 16, v133
	v_and_b32_e32 v127, 0xffff0000, v139
	v_lshlrev_b32_e32 v126, 16, v139
	v_and_b32_e32 v137, 0xffff0000, v132
	v_lshlrev_b32_e32 v136, 16, v132
	v_and_b32_e32 v133, 0xffff0000, v138
	v_lshlrev_b32_e32 v132, 16, v138
	v_and_b32_e32 v139, 0xffff0000, v177
	v_lshlrev_b32_e32 v138, 16, v177
	v_and_b32_e32 v171, 0xffff0000, v176
	v_lshlrev_b32_e32 v170, 16, v176
	v_and_b32_e32 v173, 0xffff0000, v175
	v_lshlrev_b32_e32 v172, 16, v175
	v_and_b32_e32 v169, 0xffff0000, v179
	v_lshlrev_b32_e32 v168, 16, v179
	v_and_b32_e32 v177, 0xffff0000, v174
	v_lshlrev_b32_e32 v176, 16, v174
	v_and_b32_e32 v175, 0xffff0000, v178
	v_lshlrev_b32_e32 v174, 16, v178
	v_and_b32_e32 v179, 0xffff0000, v187
	v_lshlrev_b32_e32 v178, 16, v187
	v_and_b32_e32 v183, 0xffff0000, v186
	v_lshlrev_b32_e32 v182, 16, v186
	v_and_b32_e32 v187, 0xffff0000, v195
	v_lshlrev_b32_e32 v186, 16, v195
	v_and_b32_e32 v191, 0xffff0000, v194
	v_lshlrev_b32_e32 v190, 16, v194
	v_and_b32_e32 v195, 0xffff0000, v203
	v_lshlrev_b32_e32 v194, 16, v203
	v_and_b32_e32 v199, 0xffff0000, v202
	v_lshlrev_b32_e32 v198, 16, v202
	v_and_b32_e32 v203, 0xffff0000, v211
	v_lshlrev_b32_e32 v202, 16, v211
	v_and_b32_e32 v207, 0xffff0000, v210
	v_lshlrev_b32_e32 v206, 16, v210
	v_and_b32_e32 v211, 0xffff0000, v119
	v_lshlrev_b32_e32 v210, 16, v119
	v_and_b32_e32 v213, 0xffff0000, v118
	v_lshlrev_b32_e32 v212, 16, v118
	v_and_b32_e32 v119, 0xffff0000, v117
	v_lshlrev_b32_e32 v118, 16, v117
	v_and_b32_e32 v117, 0xffff0000, v116
	v_lshlrev_b32_e32 v116, 16, v116
	v_pk_add_f32 v[104:105], v[106:107], v[104:105] op_sel_hi:[0,1]
	v_pk_fma_f32 v[104:105], v[116:117], v[116:117], v[104:105]
	v_mul_f32_e32 v106, v117, v117
	v_pk_add_f32 v[104:105], v[106:107], v[104:105] op_sel_hi:[0,1]
	v_pk_fma_f32 v[104:105], v[118:119], v[118:119], v[104:105]
	v_mul_f32_e32 v106, v119, v119
	v_pk_add_f32 v[104:105], v[106:107], v[104:105] op_sel_hi:[0,1]
	v_pk_fma_f32 v[104:105], v[212:213], v[212:213], v[104:105]
	v_mul_f32_e32 v106, v213, v213
	v_pk_add_f32 v[104:105], v[106:107], v[104:105] op_sel_hi:[0,1]
	v_pk_fma_f32 v[104:105], v[210:211], v[210:211], v[104:105]
	v_mul_f32_e32 v106, v211, v211
	v_and_b32_e32 v205, 0xffff0000, v209
	v_lshlrev_b32_e32 v204, 16, v209
	v_and_b32_e32 v209, 0xffff0000, v208
	v_lshlrev_b32_e32 v208, 16, v208
	v_pk_add_f32 v[104:105], v[106:107], v[104:105] op_sel_hi:[0,1]
	v_pk_fma_f32 v[104:105], v[208:209], v[208:209], v[104:105]
	v_mul_f32_e32 v106, v209, v209
	v_pk_add_f32 v[104:105], v[106:107], v[104:105] op_sel_hi:[0,1]
	v_pk_fma_f32 v[104:105], v[204:205], v[204:205], v[104:105]
	v_mul_f32_e32 v106, v205, v205
	v_pk_add_f32 v[104:105], v[106:107], v[104:105] op_sel_hi:[0,1]
	v_pk_fma_f32 v[104:105], v[206:207], v[206:207], v[104:105]
	v_mul_f32_e32 v106, v207, v207
	v_pk_add_f32 v[104:105], v[106:107], v[104:105] op_sel_hi:[0,1]
	v_pk_fma_f32 v[104:105], v[202:203], v[202:203], v[104:105]
	v_mul_f32_e32 v106, v203, v203
	v_and_b32_e32 v197, 0xffff0000, v201
	v_lshlrev_b32_e32 v196, 16, v201
	v_and_b32_e32 v201, 0xffff0000, v200
	v_lshlrev_b32_e32 v200, 16, v200
	v_pk_add_f32 v[104:105], v[106:107], v[104:105] op_sel_hi:[0,1]
	v_pk_fma_f32 v[104:105], v[200:201], v[200:201], v[104:105]
	v_mul_f32_e32 v106, v201, v201
	v_pk_add_f32 v[104:105], v[106:107], v[104:105] op_sel_hi:[0,1]
	v_pk_fma_f32 v[104:105], v[196:197], v[196:197], v[104:105]
	v_mul_f32_e32 v106, v197, v197
	v_pk_add_f32 v[104:105], v[106:107], v[104:105] op_sel_hi:[0,1]
	v_pk_fma_f32 v[104:105], v[198:199], v[198:199], v[104:105]
	v_mul_f32_e32 v106, v199, v199
	v_pk_add_f32 v[104:105], v[106:107], v[104:105] op_sel_hi:[0,1]
	v_pk_fma_f32 v[104:105], v[194:195], v[194:195], v[104:105]
	v_mul_f32_e32 v106, v195, v195
	v_and_b32_e32 v189, 0xffff0000, v193
	v_lshlrev_b32_e32 v188, 16, v193
	v_and_b32_e32 v193, 0xffff0000, v192
	v_lshlrev_b32_e32 v192, 16, v192
	v_pk_add_f32 v[104:105], v[106:107], v[104:105] op_sel_hi:[0,1]
	v_pk_fma_f32 v[104:105], v[192:193], v[192:193], v[104:105]
	v_mul_f32_e32 v106, v193, v193
	flat_load_dwordx4 v[100:103], v[160:161]
	flat_load_dwordx4 v[96:99], v[160:161] offset:16
	flat_load_dwordx4 v[92:95], v[160:161] offset:64
	flat_load_dwordx4 v[88:91], v[160:161] offset:80
	flat_load_dwordx4 v[84:87], v[160:161] offset:128
	flat_load_dwordx4 v[80:83], v[160:161] offset:144
	flat_load_dwordx4 v[76:79], v[160:161] offset:192
	flat_load_dwordx4 v[72:75], v[160:161] offset:208
	flat_load_dwordx4 v[68:71], v[160:161] offset:256
	flat_load_dwordx4 v[64:67], v[160:161] offset:272
	flat_load_dwordx4 v[60:63], v[160:161] offset:320
	flat_load_dwordx4 v[56:59], v[160:161] offset:336
	flat_load_dwordx4 v[52:55], v[160:161] offset:384
	flat_load_dwordx4 v[48:51], v[160:161] offset:400
	flat_load_dwordx4 v[44:47], v[160:161] offset:448
	flat_load_dwordx4 v[40:43], v[160:161] offset:464
	flat_load_dwordx4 v[36:39], v[160:161] offset:512
	flat_load_dwordx4 v[32:35], v[160:161] offset:528
	flat_load_dwordx4 v[28:31], v[160:161] offset:576
	flat_load_dwordx4 v[24:27], v[160:161] offset:592
	flat_load_dwordx4 v[20:23], v[160:161] offset:640
	flat_load_dwordx4 v[16:19], v[160:161] offset:656
	flat_load_dwordx4 v[12:15], v[160:161] offset:704
	flat_load_dwordx4 v[8:11], v[160:161] offset:720
	flat_load_dwordx4 v[4:7], v[142:143]
	flat_load_dwordx4 v[0:3], v[142:143] offset:16
; __device__ __forceinline__ void att_mfma(const Params& P, LAS unsigned char* lds, int wave) {
;     ...
;                 for (int e = 0; e < 8; ++e) { qv[ks][e] = bf2f((unsigned short)qf[ks][e]); sq += qv[ks][e] * qv[ks][e]; }
;             { const auto rr = __builtin_amdgcn_permlane32_swap(__float_as_uint(sq), __float_as_uint(sq), false, false);
;               sq = __uint_as_float(rr[0]) + __uint_as_float(rr[1]); }
;             const float rs = __builtin_amdgcn_rsqf(sq * (1.f / 192.f) + EPS) * (0.07216878364870322f * 1.4426950408889634f);
;             const float* qg = (const float*)(ws + WS_SMALL) + 2048 + 8 * hf;
;             const int spos = (int)(qrow_g & (SEQ - 1));
;             const float* cM = (const float*)(ws + WS_ROPE_M) + spos * 32 + 8 * hf; const float* sM = cM + 4096 * 32;
	v_pk_add_f32 v[104:105], v[106:107], v[104:105] op_sel_hi:[0,1]
	v_pk_fma_f32 v[104:105], v[188:189], v[188:189], v[104:105]
	v_mul_f32_e32 v106, v189, v189
	v_pk_add_f32 v[104:105], v[106:107], v[104:105] op_sel_hi:[0,1]
	v_pk_fma_f32 v[104:105], v[190:191], v[190:191], v[104:105]
	v_mul_f32_e32 v106, v191, v191
	v_pk_add_f32 v[104:105], v[106:107], v[104:105] op_sel_hi:[0,1]
	v_pk_fma_f32 v[104:105], v[186:187], v[186:187], v[104:105]
	v_mul_f32_e32 v106, v187, v187
	v_and_b32_e32 v123, 0xffff0000, v135
	v_lshlrev_b32_e32 v122, 16, v135
	v_and_b32_e32 v121, 0xffff0000, v141
	v_lshlrev_b32_e32 v120, 16, v141
	v_and_b32_e32 v129, 0xffff0000, v134
	v_lshlrev_b32_e32 v128, 16, v134
	v_and_b32_e32 v125, 0xffff0000, v140
	v_lshlrev_b32_e32 v124, 16, v140
	v_and_b32_e32 v135, 0xffff0000, v181
	v_lshlrev_b32_e32 v134, 16, v181
	v_and_b32_e32 v141, 0xffff0000, v180
	v_lshlrev_b32_e32 v140, 16, v180
	v_and_b32_e32 v181, 0xffff0000, v185
	v_lshlrev_b32_e32 v180, 16, v185
	v_and_b32_e32 v185, 0xffff0000, v184
	v_lshlrev_b32_e32 v184, 16, v184
	v_pk_add_f32 v[104:105], v[106:107], v[104:105] op_sel_hi:[0,1]
	v_pk_fma_f32 v[104:105], v[184:185], v[184:185], v[104:105]
	v_mul_f32_e32 v106, v185, v185
	v_pk_add_f32 v[104:105], v[106:107], v[104:105] op_sel_hi:[0,1]
	v_pk_fma_f32 v[104:105], v[180:181], v[180:181], v[104:105]
	v_mul_f32_e32 v106, v181, v181
	v_pk_add_f32 v[104:105], v[106:107], v[104:105] op_sel_hi:[0,1]
	v_pk_fma_f32 v[104:105], v[182:183], v[182:183], v[104:105]
	v_mul_f32_e32 v106, v183, v183
	v_pk_add_f32 v[104:105], v[106:107], v[104:105] op_sel_hi:[0,1]
	v_pk_fma_f32 v[104:105], v[178:179], v[178:179], v[104:105]
	v_mul_f32_e32 v106, v179, v179
	v_pk_add_f32 v[104:105], v[106:107], v[104:105] op_sel_hi:[0,1]
	v_pk_fma_f32 v[104:105], v[176:177], v[176:177], v[104:105]
	v_mul_f32_e32 v106, v177, v177
	v_pk_add_f32 v[104:105], v[106:107], v[104:105] op_sel_hi:[0,1]
	v_pk_fma_f32 v[104:105], v[172:173], v[172:173], v[104:105]
	v_mul_f32_e32 v106, v173, v173
	v_pk_add_f32 v[104:105], v[106:107], v[104:105] op_sel_hi:[0,1]
	v_pk_fma_f32 v[104:105], v[170:171], v[170:171], v[104:105]
	v_mul_f32_e32 v106, v171, v171
	v_pk_add_f32 v[104:105], v[106:107], v[104:105] op_sel_hi:[0,1]
	v_pk_fma_f32 v[104:105], v[138:139], v[138:139], v[104:105]
	v_mul_f32_e32 v106, v139, v139
	v_pk_add_f32 v[104:105], v[106:107], v[104:105] op_sel_hi:[0,1]
	v_pk_fma_f32 v[104:105], v[136:137], v[136:137], v[104:105]
	v_mul_f32_e32 v106, v137, v137
	v_pk_add_f32 v[104:105], v[106:107], v[104:105] op_sel_hi:[0,1]
	v_pk_fma_f32 v[104:105], v[130:131], v[130:131], v[104:105]
	v_mul_f32_e32 v106, v131, v131
	v_pk_add_f32 v[104:105], v[106:107], v[104:105] op_sel_hi:[0,1]
	v_pk_fma_f32 v[104:105], v[128:129], v[128:129], v[104:105]
	v_mul_f32_e32 v106, v129, v129
	v_pk_add_f32 v[104:105], v[106:107], v[104:105] op_sel_hi:[0,1]
	v_pk_fma_f32 v[104:105], v[122:123], v[122:123], v[104:105]
	v_mul_f32_e32 v106, v123, v123
	v_pk_add_f32 v[104:105], v[106:107], v[104:105] op_sel_hi:[0,1]
	v_pk_fma_f32 v[104:105], v[174:175], v[174:175], v[104:105]
	v_mul_f32_e32 v106, v175, v175
	v_pk_add_f32 v[104:105], v[106:107], v[104:105] op_sel_hi:[0,1]
	v_pk_fma_f32 v[104:105], v[168:169], v[168:169], v[104:105]
	v_mul_f32_e32 v106, v169, v169
	v_pk_add_f32 v[104:105], v[106:107], v[104:105] op_sel_hi:[0,1]
	v_pk_fma_f32 v[104:105], v[140:141], v[140:141], v[104:105]
	v_mul_f32_e32 v106, v141, v141
	v_pk_add_f32 v[104:105], v[106:107], v[104:105] op_sel_hi:[0,1]
	v_pk_fma_f32 v[104:105], v[134:135], v[134:135], v[104:105]
	v_mul_f32_e32 v106, v135, v135
	v_pk_add_f32 v[104:105], v[106:107], v[104:105] op_sel_hi:[0,1]
	v_pk_fma_f32 v[104:105], v[132:133], v[132:133], v[104:105]
	v_mul_f32_e32 v106, v133, v133
	v_pk_add_f32 v[104:105], v[106:107], v[104:105] op_sel_hi:[0,1]
	v_pk_fma_f32 v[104:105], v[126:127], v[126:127], v[104:105]
	v_mul_f32_e32 v106, v127, v127
	v_pk_add_f32 v[104:105], v[106:107], v[104:105] op_sel_hi:[0,1]
	v_pk_fma_f32 v[104:105], v[124:125], v[124:125], v[104:105]
	v_mul_f32_e32 v106, v125, v125
	v_pk_add_f32 v[104:105], v[106:107], v[104:105] op_sel_hi:[0,1]
	v_pk_fma_f32 v[104:105], v[120:121], v[120:121], v[104:105]
	v_mul_f32_e32 v106, v121, v121
	v_pk_add_f32 v[104:105], v[106:107], v[104:105] op_sel_hi:[0,1]
	v_mov_b32_e32 v105, v104
	s_nop 1
	v_permlane32_swap_b32_e32 v104, v105
	v_add_f32_e32 v104, v104, v105
	v_fmamk_f32 v104, v104, 0x3baaaaab, v225
	v_rsq_f32_e32 v227, v104
	flat_load_dwordx4 v[104:107], v[246:247]
	flat_load_dwordx4 v[228:231], v[246:247] offset:16
	v_mul_f32_e32 v248, 0x3dd53b94, v227
	s_waitcnt vmcnt(0) lgkmcnt(0)
; __device__ __forceinline__ void att_mfma(const Params& P, LAS unsigned char* lds, int wave) {
;     ...
; #pragma unroll
;             for (int ks = 0; ks < 12; ++ks) { const f32x4 g0 = *(const f32x4*)(qg + 16 * ks), g1 = *(const f32x4*)(qg + 16 * ks + 4);
; #pragma unroll
;                 for (int e = 0; e < 4; ++e) { qv[ks][e] *= rs * g0[e]; qv[ks][4 + e] *= rs * g1[e]; } }
; #pragma unroll
;             for (int k2 = 0; k2 < 2; ++k2) {
;                 const f32x4 c0 = *(const f32x4*)(cM + 16 * k2), c1 = *(const f32x4*)(cM + 16 * k2 + 4), s0 = *(const f32x4*)(sM + 16 * k2), s1 = *(const f32x4*)(sM + 16 * k2 + 4);
; #pragma unroll
;                 for (int e = 0; e < 8; ++e) { const float cc = e < 4 ? c0[e & 3] : c1[e & 3], ss = e < 4 ? s0[e & 3] : s1[e & 3];
;                     const float a = qv[8 + k2][e], bq = qv[10 + k2][e]; qv[8 + k2][e] = a * cc - bq * ss; qv[10 + k2][e] = bq * cc + a * ss; }
;             }
	v_pk_mul_f32 v[96:97], v[96:97], v[248:249] op_sel_hi:[1,0]
	v_pk_mul_f32 v[100:101], v[100:101], v[248:249] op_sel_hi:[1,0]
	v_pk_mul_f32 v[252:253], v[96:97], v[232:233]
	v_pk_mul_f32 v[96:97], v[102:103], v[248:249] op_sel_hi:[1,0]
	v_pk_mul_f32 v[250:251], v[100:101], v[234:235]
	flat_load_dwordx4 v[232:235], v[142:143] offset:64
	flat_load_dwordx4 v[236:239], v[142:143] offset:80
	v_pk_mul_f32 v[142:143], v[96:97], v[242:243]
	v_pk_mul_f32 v[242:243], v[98:99], v[248:249] op_sel_hi:[1,0]
	flat_load_dwordx4 v[96:99], v[246:247] offset:64
	flat_load_dwordx4 v[100:103], v[246:247] offset:80
	v_pk_mul_f32 v[20:21], v[248:249], v[20:21] op_sel_hi:[0,1]
	v_pk_mul_f32 v[92:93], v[92:93], v[248:249] op_sel_hi:[1,0]
	v_pk_mul_f32 v[36:37], v[248:249], v[36:37] op_sel_hi:[0,1]
	v_pk_mul_f32 v[20:21], v[20:21], v[174:175]
	v_pk_mul_f32 v[92:93], v[92:93], v[108:109]
	v_pk_mul_f32 v[36:37], v[36:37], v[176:177]
	v_pk_mul_f32 v[38:39], v[248:249], v[38:39] op_sel_hi:[0,1]
	v_pk_mul_f32 v[24:25], v[248:249], v[24:25] op_sel_hi:[0,1]
	v_pk_mul_f32 v[22:23], v[248:249], v[22:23] op_sel_hi:[0,1]
	v_pk_mul_f32 v[38:39], v[38:39], v[172:173]
	v_pk_mul_f32 v[24:25], v[24:25], v[128:129]
	v_pk_mul_f32 v[16:17], v[248:249], v[16:17] op_sel_hi:[0,1]
	v_pk_mul_f32 v[22:23], v[22:23], v[168:169]
	v_pk_mul_f32 v[32:33], v[248:249], v[32:33] op_sel_hi:[0,1]
	v_pk_mul_f32 v[16:17], v[16:17], v[140:141]
	v_pk_mul_f32 v[32:33], v[32:33], v[170:171]
	v_pk_mul_f32 v[34:35], v[248:249], v[34:35] op_sel_hi:[0,1]
	v_pk_mul_f32 v[18:19], v[248:249], v[18:19] op_sel_hi:[0,1]
	v_pk_mul_f32 v[34:35], v[34:35], v[138:139]
	v_pk_mul_f32 v[18:19], v[18:19], v[134:135]
	v_pk_mul_f32 v[12:13], v[248:249], v[12:13] op_sel_hi:[0,1]
	v_pk_mul_f32 v[28:29], v[248:249], v[28:29] op_sel_hi:[0,1]
	v_pk_mul_f32 v[12:13], v[12:13], v[132:133]
	v_pk_mul_f32 v[28:29], v[28:29], v[136:137]
	v_pk_mul_f32 v[14:15], v[248:249], v[14:15] op_sel_hi:[0,1]
	v_pk_mul_f32 v[30:31], v[248:249], v[30:31] op_sel_hi:[0,1]
	v_pk_mul_f32 v[14:15], v[14:15], v[126:127]
	v_pk_mul_f32 v[30:31], v[30:31], v[130:131]
	v_pk_mul_f32 v[8:9], v[248:249], v[8:9] op_sel_hi:[0,1]
	v_pk_mul_f32 v[8:9], v[8:9], v[124:125]
	v_pk_mul_f32 v[10:11], v[248:249], v[10:11] op_sel_hi:[0,1]
	v_pk_mul_f32 v[26:27], v[248:249], v[26:27] op_sel_hi:[0,1]
	v_pk_mul_f32 v[10:11], v[10:11], v[120:121]
	v_pk_mul_f32 v[26:27], v[26:27], v[122:123]
	v_pk_mul_f32 v[60:61], v[248:249], v[60:61] op_sel_hi:[0,1]
	v_pk_mul_f32 v[56:57], v[248:249], v[56:57] op_sel_hi:[0,1]
	v_pk_mul_f32 v[62:63], v[248:249], v[62:63] op_sel_hi:[0,1]
	v_pk_mul_f32 v[58:59], v[248:249], v[58:59] op_sel_hi:[0,1]
	v_pk_mul_f32 v[52:53], v[248:249], v[52:53] op_sel_hi:[0,1]
	v_pk_mul_f32 v[48:49], v[248:249], v[48:49] op_sel_hi:[0,1]
	v_pk_mul_f32 v[54:55], v[248:249], v[54:55] op_sel_hi:[0,1]
	v_pk_mul_f32 v[50:51], v[248:249], v[50:51] op_sel_hi:[0,1]
	v_pk_mul_f32 v[44:45], v[248:249], v[44:45] op_sel_hi:[0,1]
	v_pk_mul_f32 v[40:41], v[248:249], v[40:41] op_sel_hi:[0,1]
	v_pk_mul_f32 v[46:47], v[248:249], v[46:47] op_sel_hi:[0,1]
	v_pk_mul_f32 v[42:43], v[248:249], v[42:43] op_sel_hi:[0,1]
	v_pk_mul_f32 v[88:89], v[88:89], v[248:249] op_sel_hi:[1,0]
	v_pk_mul_f32 v[94:95], v[94:95], v[248:249] op_sel_hi:[1,0]
	v_pk_mul_f32 v[90:91], v[90:91], v[248:249] op_sel_hi:[1,0]
	v_pk_mul_f32 v[84:85], v[84:85], v[248:249] op_sel_hi:[1,0]
	v_pk_mul_f32 v[80:81], v[248:249], v[80:81] op_sel_hi:[0,1]
	v_pk_mul_f32 v[86:87], v[86:87], v[248:249] op_sel_hi:[1,0]
	v_pk_mul_f32 v[82:83], v[248:249], v[82:83] op_sel_hi:[0,1]
	v_pk_mul_f32 v[76:77], v[248:249], v[76:77] op_sel_hi:[0,1]
	v_pk_mul_f32 v[72:73], v[248:249], v[72:73] op_sel_hi:[0,1]
	v_pk_mul_f32 v[78:79], v[248:249], v[78:79] op_sel_hi:[0,1]
	v_pk_mul_f32 v[74:75], v[248:249], v[74:75] op_sel_hi:[0,1]
	v_pk_mul_f32 v[68:69], v[248:249], v[68:69] op_sel_hi:[0,1]
	v_pk_mul_f32 v[64:65], v[248:249], v[64:65] op_sel_hi:[0,1]
	v_pk_mul_f32 v[70:71], v[248:249], v[70:71] op_sel_hi:[0,1]
	v_pk_mul_f32 v[66:67], v[248:249], v[66:67] op_sel_hi:[0,1]
	v_pk_mul_f32 v[60:61], v[60:61], v[200:201]
	v_pk_mul_f32 v[56:57], v[56:57], v[198:199]
	v_pk_mul_f32 v[62:63], v[62:63], v[196:197]
	v_pk_mul_f32 v[58:59], v[58:59], v[194:195]
	v_pk_mul_f32 v[52:53], v[52:53], v[192:193]
	v_pk_mul_f32 v[108:109], v[20:21], v[104:105]
	v_pk_mul_f32 v[48:49], v[48:49], v[190:191]
	v_pk_fma_f32 v[128:129], v[36:37], v[4:5], v[108:109] neg_lo:[0,0,1] neg_hi:[0,0,1]
	v_pk_mul_f32 v[36:37], v[36:37], v[104:105]
	v_pk_mul_f32 v[54:55], v[54:55], v[188:189]
	v_pk_fma_f32 v[4:5], v[20:21], v[4:5], v[36:37]
	v_pk_mul_f32 v[20:21], v[22:23], v[106:107]
	v_pk_mul_f32 v[36:37], v[38:39], v[106:107]
	v_pk_fma_f32 v[20:21], v[38:39], v[6:7], v[20:21] neg_lo:[0,0,1] neg_hi:[0,0,1]
	v_pk_fma_f32 v[6:7], v[22:23], v[6:7], v[36:37]
	v_pk_mul_f32 v[22:23], v[16:17], v[228:229]
	v_pk_mul_f32 v[50:51], v[50:51], v[186:187]
	v_pk_fma_f32 v[22:23], v[32:33], v[0:1], v[22:23] neg_lo:[0,0,1] neg_hi:[0,0,1]
	v_pk_mul_f32 v[32:33], v[32:33], v[228:229]
	v_pk_mul_f32 v[44:45], v[44:45], v[184:185]
	v_pk_fma_f32 v[0:1], v[16:17], v[0:1], v[32:33]
	v_pk_mul_f32 v[16:17], v[18:19], v[230:231]
	v_pk_mul_f32 v[32:33], v[34:35], v[230:231]
	v_pk_fma_f32 v[16:17], v[34:35], v[2:3], v[16:17] neg_lo:[0,0,1] neg_hi:[0,0,1]
	v_pk_fma_f32 v[2:3], v[18:19], v[2:3], v[32:33]
	s_waitcnt vmcnt(0) lgkmcnt(0)
; __device__ __forceinline__ void att_mfma(const Params& P, LAS unsigned char* lds, int wave) {
;     ...
;         f32x16 o[4];
; #pragma unroll
;         for (int d = 0; d < 4; ++d)
; #pragma unroll
;             for (int i = 0; i < 16; ++i) o[d][i] = 0.f;
;         float mrun = -1e30f, lrun = 0.f;
;         bf16x8 pb[4];
; #pragma unroll
;         for (int i = 0; i < 4; ++i) pb[i] = (bf16x8){0, 0, 0, 0, 0, 0, 0, 0};
;     ...
;             for (int ks = 0; ks < 12; ++ks) qf[ks] = pack8bf(qv[ks][0], qv[ks][1], qv[ks][2], qv[ks][3], qv[ks][4], qv[ks][5], qv[ks][6], qv[ks][7]);
;         }
;         int bcur = 0, bprev = 2, bnext = 1;
; #pragma unroll 1
;         for (int kt = 0; kt < ntile; ++kt) {
	v_pk_mul_f32 v[18:19], v[12:13], v[96:97]
	v_pk_mul_f32 v[40:41], v[40:41], v[182:183]
	v_pk_fma_f32 v[18:19], v[28:29], v[232:233], v[18:19] neg_lo:[0,0,1] neg_hi:[0,0,1]
	v_pk_mul_f32 v[28:29], v[28:29], v[96:97]
	v_pk_mul_f32 v[46:47], v[46:47], v[180:181]
	v_pk_fma_f32 v[12:13], v[12:13], v[232:233], v[28:29]
	v_pk_mul_f32 v[28:29], v[14:15], v[98:99]
	v_pk_mul_f32 v[42:43], v[42:43], v[178:179]
	v_pk_fma_f32 v[28:29], v[30:31], v[234:235], v[28:29] neg_lo:[0,0,1] neg_hi:[0,0,1]
	v_pk_mul_f32 v[30:31], v[30:31], v[98:99]
	v_pk_mul_f32 v[240:241], v[242:243], v[240:241]
	v_pk_fma_f32 v[14:15], v[14:15], v[234:235], v[30:31]
	v_pk_mul_f32 v[30:31], v[8:9], v[100:101]
	v_cvt_pk_bf16_f32 v141, v14, v15
	v_pk_fma_f32 v[30:31], v[24:25], v[236:237], v[30:31] neg_lo:[0,0,1] neg_hi:[0,0,1]
	v_pk_mul_f32 v[24:25], v[24:25], v[100:101]
	v_mov_b32_e32 v14, v165
	v_pk_fma_f32 v[8:9], v[8:9], v[236:237], v[24:25]
	v_pk_mul_f32 v[24:25], v[10:11], v[102:103]
	v_mov_b32_e32 v15, v165
	v_pk_fma_f32 v[24:25], v[26:27], v[238:239], v[24:25] neg_lo:[0,0,1] neg_hi:[0,0,1]
	v_pk_mul_f32 v[26:27], v[26:27], v[102:103]
	v_pk_mul_f32 v[88:89], v[88:89], v[220:221]
	v_pk_fma_f32 v[10:11], v[10:11], v[238:239], v[26:27]
	v_pk_mul_f32 v[94:95], v[94:95], v[110:111]
	v_pk_mul_f32 v[90:91], v[90:91], v[218:219]
	v_pk_mul_f32 v[84:85], v[84:85], v[112:113]
	v_pk_mul_f32 v[80:81], v[80:81], v[216:217]
	v_pk_mul_f32 v[86:87], v[86:87], v[114:115]
	v_pk_mul_f32 v[82:83], v[82:83], v[214:215]
	v_pk_mul_f32 v[76:77], v[76:77], v[116:117]
	v_pk_mul_f32 v[72:73], v[72:73], v[212:213]
	v_pk_mul_f32 v[78:79], v[78:79], v[118:119]
	v_pk_mul_f32 v[74:75], v[74:75], v[210:211]
	v_pk_mul_f32 v[68:69], v[68:69], v[208:209]
	v_pk_mul_f32 v[64:65], v[64:65], v[206:207]
	v_pk_mul_f32 v[70:71], v[70:71], v[204:205]
	v_pk_mul_f32 v[66:67], v[66:67], v[202:203]
	v_cvt_pk_bf16_f32 v97, v142, v143
	v_cvt_pk_bf16_f32 v116, v60, v61
	v_cvt_pk_bf16_f32 v117, v62, v63
	v_cvt_pk_bf16_f32 v118, v56, v57
	v_cvt_pk_bf16_f32 v119, v58, v59
	v_cvt_pk_bf16_f32 v120, v52, v53
	v_cvt_pk_bf16_f32 v121, v54, v55
	v_cvt_pk_bf16_f32 v122, v48, v49
	v_cvt_pk_bf16_f32 v123, v50, v51
	v_cvt_pk_bf16_f32 v124, v44, v45
	v_cvt_pk_bf16_f32 v125, v46, v47
	v_cvt_pk_bf16_f32 v126, v40, v41
	v_cvt_pk_bf16_f32 v127, v42, v43
	v_cvt_pk_bf16_f32 v128, v128, v129
	v_cvt_pk_bf16_f32 v129, v20, v21
	v_cvt_pk_bf16_f32 v130, v22, v23
	v_cvt_pk_bf16_f32 v131, v16, v17
	v_cvt_pk_bf16_f32 v132, v18, v19
	v_cvt_pk_bf16_f32 v133, v28, v29
	v_cvt_pk_bf16_f32 v134, v30, v31
	v_cvt_pk_bf16_f32 v135, v24, v25
	v_cvt_pk_bf16_f32 v136, v4, v5
	v_cvt_pk_bf16_f32 v137, v6, v7
	v_cvt_pk_bf16_f32 v138, v0, v1
	v_cvt_pk_bf16_f32 v139, v2, v3
	v_cvt_pk_bf16_f32 v140, v12, v13
	v_cvt_pk_bf16_f32 v142, v8, v9
	v_cvt_pk_bf16_f32 v143, v10, v11
	v_mov_b32_e32 v0, v165
	v_mov_b32_e32 v1, v165
	v_mov_b32_e32 v2, v165
	v_mov_b32_e32 v3, v165
	v_mov_b32_e32 v4, v165
	v_mov_b32_e32 v5, v165
	v_mov_b32_e32 v6, v165
	v_mov_b32_e32 v7, v165
	v_mov_b32_e32 v8, v165
	v_mov_b32_e32 v9, v165
	v_mov_b32_e32 v10, v165
	v_mov_b32_e32 v11, v165
	v_mov_b32_e32 v12, v165
	v_mov_b32_e32 v13, v165
	v_mov_b64_e32 v[30:31], v[14:15]
	v_mov_b64_e32 v[46:47], v[14:15]
	v_mov_b64_e32 v[62:63], v[14:15]
	v_cvt_pk_bf16_f32 v96, v250, v251
	v_cvt_pk_bf16_f32 v98, v252, v253
	v_cvt_pk_bf16_f32 v99, v240, v241
	v_cvt_pk_bf16_f32 v100, v92, v93
	v_cvt_pk_bf16_f32 v101, v94, v95
	v_cvt_pk_bf16_f32 v102, v88, v89
	v_cvt_pk_bf16_f32 v103, v90, v91
	v_cvt_pk_bf16_f32 v104, v84, v85
	v_cvt_pk_bf16_f32 v105, v86, v87
	v_cvt_pk_bf16_f32 v106, v80, v81
	v_cvt_pk_bf16_f32 v107, v82, v83
	v_cvt_pk_bf16_f32 v108, v76, v77
	v_cvt_pk_bf16_f32 v109, v78, v79
	v_cvt_pk_bf16_f32 v110, v72, v73
	v_cvt_pk_bf16_f32 v111, v74, v75
	v_cvt_pk_bf16_f32 v112, v68, v69
	v_cvt_pk_bf16_f32 v113, v70, v71
	v_cvt_pk_bf16_f32 v114, v64, v65
	v_cvt_pk_bf16_f32 v115, v66, v67
	v_mov_b32_e32 v169, 0xf149f2ca
	v_mov_b32_e32 v168, 0
	v_mov_b32_e32 v64, 0
	v_mov_b32_e32 v65, 0
	v_mov_b32_e32 v66, 0
	v_mov_b32_e32 v67, 0
	v_mov_b32_e32 v68, 0
	v_mov_b32_e32 v69, 0
	v_mov_b32_e32 v70, 0
	v_mov_b32_e32 v71, 0
	v_mov_b32_e32 v72, 0
	v_mov_b32_e32 v73, 0
	v_mov_b32_e32 v74, 0
	v_mov_b32_e32 v75, 0
	v_mov_b32_e32 v76, 0
	v_mov_b32_e32 v77, 0
	v_mov_b32_e32 v78, 0
	v_mov_b32_e32 v79, 0
	v_mov_b64_e32 v[28:29], v[12:13]
	v_mov_b64_e32 v[26:27], v[10:11]
	v_mov_b64_e32 v[24:25], v[8:9]
	v_mov_b64_e32 v[22:23], v[6:7]
	v_mov_b64_e32 v[20:21], v[4:5]
	v_mov_b64_e32 v[18:19], v[2:3]
	v_mov_b64_e32 v[16:17], v[0:1]
	v_mov_b64_e32 v[44:45], v[12:13]
	v_mov_b64_e32 v[42:43], v[10:11]
	v_mov_b64_e32 v[40:41], v[8:9]
	v_mov_b64_e32 v[38:39], v[6:7]
	v_mov_b64_e32 v[36:37], v[4:5]
	v_mov_b64_e32 v[34:35], v[2:3]
	v_mov_b64_e32 v[32:33], v[0:1]
	v_mov_b64_e32 v[60:61], v[12:13]
	v_mov_b64_e32 v[58:59], v[10:11]
	v_mov_b64_e32 v[56:57], v[8:9]
	v_mov_b64_e32 v[54:55], v[6:7]
	v_mov_b64_e32 v[52:53], v[4:5]
	v_mov_b64_e32 v[50:51], v[2:3]
	v_mov_b64_e32 v[48:49], v[0:1]
	s_add_i32 s60, s16, 1
	s_cmp_ge_u32 s60, s50
	s_mov_b32 s59, s61
	s_cbranch_scc1 .LBB0_1016

; #define LAS __attribute__((address_space(3)))
; #define TR_READ(dst, addr, off) asm volatile("ds_read_b64_tr_b16 %0, %1 offset:%c2" : "=v"(dst) : "v"(addr), "i"(off) : "memory")
; #define TR_WAIT4(n, a, b, c, d) asm volatile("s_waitcnt lgkmcnt(" #n ")" : "+v"(a), "+v"(b), "+v"(c), "+v"(d) :: "memory")
; __device__ __forceinline__ void att_pv(const LAS unsigned char* kb, int vlane, const bf16x8 (&pb)[4], f32x16 (&o)[4]) {
;     constexpr int VP = 320;
;     s16x4 vlo[2][4], vhi[2][4];
;     const unsigned vaddr = (unsigned)(unsigned long)(kb + vlane);
; #pragma unroll
;     for (int d = 0; d < 4; ++d) { TR_READ(vlo[0][d], vaddr, d * 64); TR_READ(vhi[0][d], vaddr, 8 * VP + d * 64); }
; #pragma unroll
;     for (int ks = 0; ks < 4; ++ks) {
;         if (ks < 3) {
; #pragma unroll
;             for (int d = 0; d < 4; ++d) { TR_READ(vlo[(ks + 1) & 1][d], vaddr, ((ks + 1) * 16) * VP + d * 64); TR_READ(vhi[(ks + 1) & 1][d], vaddr, ((ks + 1) * 16 + 8) * VP + d * 64); }
;             TR_WAIT4(8, vlo[ks & 1][0], vlo[ks & 1][1], vlo[ks & 1][2], vlo[ks & 1][3]); TR_WAIT4(8, vhi[ks & 1][0], vhi[ks & 1][1], vhi[ks & 1][2], vhi[ks & 1][3]);
;         } else {
;             TR_WAIT4(0, vlo[ks & 1][0], vlo[ks & 1][1], vlo[ks & 1][2], vlo[ks & 1][3]); TR_WAIT4(0, vhi[ks & 1][0], vhi[ks & 1][1], vhi[ks & 1][2], vhi[ks & 1][3]);
;         }
;         __builtin_amdgcn_sched_barrier(0);
; #pragma unroll
;         for (int d = 0; d < 4; ++d) { const bf16x8 a = __builtin_shufflevector(vlo[ks & 1][d], vhi[ks & 1][d], 0, 1, 2, 3, 4, 5, 6, 7);
;             o[d] = __builtin_amdgcn_mfma_f32_32x32x16_bf16(a, pb[ks], o[d], 0, 0, 0); }
;         __builtin_amdgcn_sched_barrier(0);
;     }
; }
; __device__ __forceinline__ void att_mfma(const Params& P, LAS unsigned char* lds, int wave) {
;     ...
;             if (!roleA && kt >= 1 && kt - 1 <= my_last) att_pv(lds + bprev * BUF, vlane, pb, o);
.LBB0_1016:
	s_cmp_gt_u32 s16, s76
	s_cselect_b64 s[4:5], -1, 0
	s_and_b64 s[4:5], s[0:1], s[4:5]
	s_cmp_le_u32 s16, s51
	s_cselect_b64 s[62:63], -1, 0
	s_and_b64 s[4:5], s[4:5], s[62:63]
	s_andn2_b64 vcc, exec, s[4:5]
	s_cbranch_vccnz .LBB0_1018
	s_mul_i32 s4, s17, 0xb400
	v_add_u32_e32 v80, s4, v222
	v_add_u32_e32 v186, 0x6400, v80
	ds_read_b64_tr_b16 v[80:81], v186 offset:0
	ds_read_b64_tr_b16 v[82:83], v186 offset:2560
	ds_read_b64_tr_b16 v[84:85], v186 offset:64
	ds_read_b64_tr_b16 v[86:87], v186 offset:2624
	ds_read_b64_tr_b16 v[88:89], v186 offset:128
	ds_read_b64_tr_b16 v[90:91], v186 offset:2688
	ds_read_b64_tr_b16 v[92:93], v186 offset:192
	ds_read_b64_tr_b16 v[94:95], v186 offset:2752
	ds_read_b64_tr_b16 v[170:171], v186 offset:5120
	ds_read_b64_tr_b16 v[172:173], v186 offset:7680
	ds_read_b64_tr_b16 v[174:175], v186 offset:5184
	ds_read_b64_tr_b16 v[176:177], v186 offset:7744
	ds_read_b64_tr_b16 v[178:179], v186 offset:5248
	ds_read_b64_tr_b16 v[180:181], v186 offset:7808
	ds_read_b64_tr_b16 v[182:183], v186 offset:5312
	ds_read_b64_tr_b16 v[184:185], v186 offset:7872
	s_nop 0
	s_waitcnt lgkmcnt(8)
	s_waitcnt lgkmcnt(8)
	s_nop 0
	v_mfma_f32_32x32x16_bf16 v[48:63], v[80:83], v[76:79], v[48:63]
	v_mfma_f32_32x32x16_bf16 v[32:47], v[84:87], v[76:79], v[32:47]
	v_mfma_f32_32x32x16_bf16 v[16:31], v[88:91], v[76:79], v[16:31]
	v_mfma_f32_32x32x16_bf16 v[0:15], v[92:95], v[76:79], v[0:15]
	ds_read_b64_tr_b16 v[80:81], v186 offset:10240
	ds_read_b64_tr_b16 v[82:83], v186 offset:12800
	ds_read_b64_tr_b16 v[84:85], v186 offset:10304
	ds_read_b64_tr_b16 v[86:87], v186 offset:12864
	ds_read_b64_tr_b16 v[88:89], v186 offset:10368
	ds_read_b64_tr_b16 v[90:91], v186 offset:12928
	ds_read_b64_tr_b16 v[92:93], v186 offset:10432
	ds_read_b64_tr_b16 v[94:95], v186 offset:12992
	s_waitcnt lgkmcnt(8)
	s_waitcnt lgkmcnt(8)
	s_nop 0
	v_mfma_f32_32x32x16_bf16 v[48:63], v[170:173], v[72:75], v[48:63]
	v_mfma_f32_32x32x16_bf16 v[32:47], v[174:177], v[72:75], v[32:47]
	v_mfma_f32_32x32x16_bf16 v[16:31], v[178:181], v[72:75], v[16:31]
	v_mfma_f32_32x32x16_bf16 v[0:15], v[182:185], v[72:75], v[0:15]
	ds_read_b64_tr_b16 v[170:171], v186 offset:15360
	ds_read_b64_tr_b16 v[172:173], v186 offset:17920
	ds_read_b64_tr_b16 v[174:175], v186 offset:15424
	ds_read_b64_tr_b16 v[176:177], v186 offset:17984
	ds_read_b64_tr_b16 v[178:179], v186 offset:15488
	ds_read_b64_tr_b16 v[180:181], v186 offset:18048
	ds_read_b64_tr_b16 v[182:183], v186 offset:15552
	ds_read_b64_tr_b16 v[184:185], v186 offset:18112
	s_waitcnt lgkmcnt(8)
	s_waitcnt lgkmcnt(8)
	s_nop 0
	v_mfma_f32_32x32x16_bf16 v[48:63], v[80:83], v[68:71], v[48:63]
	v_mfma_f32_32x32x16_bf16 v[32:47], v[84:87], v[68:71], v[32:47]
	v_mfma_f32_32x32x16_bf16 v[16:31], v[88:91], v[68:71], v[16:31]
	v_mfma_f32_32x32x16_bf16 v[0:15], v[92:95], v[68:71], v[0:15]
	s_waitcnt lgkmcnt(0)
	s_waitcnt lgkmcnt(0)
	s_nop 0
	v_mfma_f32_32x32x16_bf16 v[48:63], v[170:173], v[64:67], v[48:63]
	v_mfma_f32_32x32x16_bf16 v[32:47], v[174:177], v[64:67], v[32:47]
	v_mfma_f32_32x32x16_bf16 v[16:31], v[178:181], v[64:67], v[16:31]
	v_mfma_f32_32x32x16_bf16 v[0:15], v[182:185], v[64:67], v[0:15]
; #define LAS __attribute__((address_space(3)))
; __device__ __forceinline__ void att_qk_sm(const LAS unsigned char* kb, int klane, const bf16x8 (&qf)[12], f32x16 (&o)[4], float& mrun, float& lrun, bf16x8 (&pb)[4]) {
;     constexpr int KP = 400;
;     f32x16 s0, s1;
; #pragma unroll
;     for (int i = 0; i < 16; ++i) { s0[i] = 0.f; s1[i] = 0.f; }
;     bf16x8 ka[3][2];
; #pragma unroll
;     for (int g = 0; g < 2; ++g) { ka[g][0] = *(const LAS bf16x8*)(kb + klane + g * 32); ka[g][1] = *(const LAS bf16x8*)(kb + klane + 32 * KP + g * 32); }
; #pragma unroll
;     for (int g = 0; g < 12; ++g) {
;         if (g < 10) { ka[(g + 2) % 3][0] = *(const LAS bf16x8*)(kb + klane + (g + 2) * 32); ka[(g + 2) % 3][1] = *(const LAS bf16x8*)(kb + klane + 32 * KP + (g + 2) * 32); }
;         __builtin_amdgcn_sched_barrier(0);
;         s0 = __builtin_amdgcn_mfma_f32_32x32x16_bf16(ka[g % 3][0], qf[g], s0, 0, 0, 0);
;         s1 = __builtin_amdgcn_mfma_f32_32x32x16_bf16(ka[g % 3][1], qf[g], s1, 0, 0, 0);
;         __builtin_amdgcn_sched_barrier(0);
;     }
;     float mx = fmaxf(s0[0], s1[0]);
; #pragma unroll
;     for (int i = 1; i < 16; ++i) asm("v_max3_f32 %0, %1, %2, %3" : "=v"(mx) : "v"(mx), "v"(s0[i]), "v"(s1[i]));
;     { const auto rr = __builtin_amdgcn_permlane32_swap(__float_as_uint(mx), __float_as_uint(mx), false, false);
;       mx = fmaxf(__uint_as_float(rr[0]), __uint_as_float(rr[1])); }
;     if (!__all(mx - mrun <= 8.0f)) {
;         const float mn = fmaxf(mrun, mx), al = __builtin_amdgcn_exp2f(mrun - mn);
;         mrun = mn; lrun *= al;
; #pragma unroll
;         for (int d = 0; d < 4; ++d) o[d] = o[d] * al;
;     }
.LBB0_1018:
	s_cmp_gt_u32 s16, s6
	s_cselect_b64 s[62:63], -1, 0
	s_cmp_lt_u32 s16, s76
	s_cselect_b64 s[16:17], -1, 0
	s_or_b64 s[16:17], s[16:17], s[62:63]
	s_and_b64 vcc, exec, s[16:17]
	s_mul_i32 s61, s58, 0xb400
	s_cbranch_vccnz .LBB0_1022
	v_add_u32_e32 v194, s61, v223
	ds_read_b128 v[64:67], v194
	ds_read_b128 v[170:173], v194 offset:32
	ds_read_b128 v[174:177], v194 offset:12832
	ds_read_b128 v[178:181], v194 offset:12864
	ds_read_b128 v[182:185], v194 offset:64
	ds_read_b128 v[68:71], v194 offset:12800
	s_waitcnt lgkmcnt(0)
	v_mfma_f32_32x32x16_bf16 v[80:95], v[64:67], v[96:99], 0
	v_mfma_f32_32x32x16_bf16 v[64:79], v[68:71], v[96:99], 0
	ds_read_b128 v[186:189], v194 offset:96
	ds_read_b128 v[190:193], v194 offset:12896
	v_mfma_f32_32x32x16_bf16 v[80:95], v[170:173], v[100:103], v[80:95]
	v_mfma_f32_32x32x16_bf16 v[64:79], v[174:177], v[100:103], v[64:79]
	ds_read_b128 v[170:173], v194 offset:128
	ds_read_b128 v[174:177], v194 offset:12928
	v_mfma_f32_32x32x16_bf16 v[80:95], v[182:185], v[104:107], v[80:95]
	v_mfma_f32_32x32x16_bf16 v[64:79], v[178:181], v[104:107], v[64:79]
	ds_read_b128 v[178:181], v194 offset:160
	ds_read_b128 v[182:185], v194 offset:12960
	s_waitcnt lgkmcnt(0)
	v_mfma_f32_32x32x16_bf16 v[80:95], v[186:189], v[108:111], v[80:95]
	v_mfma_f32_32x32x16_bf16 v[64:79], v[190:193], v[108:111], v[64:79]
	ds_read_b128 v[186:189], v194 offset:192
	ds_read_b128 v[190:193], v194 offset:12992
	v_mfma_f32_32x32x16_bf16 v[80:95], v[170:173], v[112:115], v[80:95]
	v_mfma_f32_32x32x16_bf16 v[64:79], v[174:177], v[112:115], v[64:79]
	ds_read_b128 v[170:173], v194 offset:224
	ds_read_b128 v[174:177], v194 offset:13024
	v_mfma_f32_32x32x16_bf16 v[80:95], v[178:181], v[116:119], v[80:95]
	v_mfma_f32_32x32x16_bf16 v[64:79], v[182:185], v[116:119], v[64:79]
	ds_read_b128 v[178:181], v194 offset:256
	ds_read_b128 v[182:185], v194 offset:13056
	s_waitcnt lgkmcnt(0)
	v_mfma_f32_32x32x16_bf16 v[80:95], v[186:189], v[120:123], v[80:95]
	v_mfma_f32_32x32x16_bf16 v[64:79], v[190:193], v[120:123], v[64:79]
	ds_read_b128 v[186:189], v194 offset:288
	ds_read_b128 v[190:193], v194 offset:13088
	v_mfma_f32_32x32x16_bf16 v[80:95], v[170:173], v[124:127], v[80:95]
	v_mfma_f32_32x32x16_bf16 v[64:79], v[174:177], v[124:127], v[64:79]
	ds_read_b128 v[170:173], v194 offset:320
	ds_read_b128 v[174:177], v194 offset:13120
	v_mfma_f32_32x32x16_bf16 v[80:95], v[178:181], v[128:131], v[80:95]
	v_mfma_f32_32x32x16_bf16 v[64:79], v[182:185], v[128:131], v[64:79]
	ds_read_b128 v[178:181], v194 offset:352
	ds_read_b128 v[182:185], v194 offset:13152
	s_waitcnt lgkmcnt(0)
	v_mfma_f32_32x32x16_bf16 v[80:95], v[186:189], v[132:135], v[80:95]
	v_mfma_f32_32x32x16_bf16 v[64:79], v[190:193], v[132:135], v[64:79]
	v_mfma_f32_32x32x16_bf16 v[80:95], v[170:173], v[136:139], v[80:95]
	v_mfma_f32_32x32x16_bf16 v[64:79], v[174:177], v[136:139], v[64:79]
	v_mfma_f32_32x32x16_bf16 v[80:95], v[178:181], v[140:143], v[80:95]
	v_mfma_f32_32x32x16_bf16 v[64:79], v[182:185], v[140:143], v[64:79]
	s_nop 11
	v_max_f32_e32 v170, v64, v64
	v_max_f32_e32 v171, v80, v80
	v_max_f32_e32 v170, v171, v170
	v_max3_f32 v170, v170, v81, v65
	s_nop 0
	v_max3_f32 v170, v170, v82, v66
	s_nop 0
	v_max3_f32 v170, v170, v83, v67
	s_nop 0
	v_max3_f32 v170, v170, v84, v68
	s_nop 0
	v_max3_f32 v170, v170, v85, v69
	s_nop 0
	v_max3_f32 v170, v170, v86, v70
	s_nop 0
	v_max3_f32 v170, v170, v87, v71
	s_nop 0
	v_max3_f32 v170, v170, v88, v72
	s_nop 0
	v_max3_f32 v170, v170, v89, v73
	s_nop 0
	v_max3_f32 v170, v170, v90, v74
	s_nop 0
	v_max3_f32 v170, v170, v91, v75
	s_nop 0
	v_max3_f32 v170, v170, v92, v76
	s_nop 0
	v_max3_f32 v170, v170, v93, v77
	s_nop 0
	v_max3_f32 v170, v170, v94, v78
	s_nop 0
	v_max3_f32 v170, v170, v95, v79
	s_nop 0
	v_mov_b32_e32 v171, v170
	s_nop 1
	v_permlane32_swap_b32_e32 v170, v171
	v_max_f32_e32 v171, v171, v171
	v_max_f32_e32 v170, v170, v170
	v_max_f32_e32 v170, v170, v171
	v_sub_f32_e32 v171, v170, v169
	v_cmp_ge_f32_e32 vcc, s37, v171
	s_cmp_eq_u64 vcc, exec
	s_cbranch_scc1 .LBB0_1021
	v_max_f32_e32 v170, v170, v170
	v_max_f32_e32 v171, v169, v169
	v_max_f32_e32 v171, v171, v170
	v_sub_f32_e32 v169, v169, v171
	v_exp_f32_e32 v170, v169
	v_mov_b32_e32 v169, v171
	v_mul_f32_e32 v168, v168, v170
	v_pk_mul_f32 v[62:63], v[62:63], v[170:171] op_sel_hi:[1,0]
	v_pk_mul_f32 v[60:61], v[60:61], v[170:171] op_sel_hi:[1,0]
	v_pk_mul_f32 v[58:59], v[58:59], v[170:171] op_sel_hi:[1,0]
	v_pk_mul_f32 v[56:57], v[56:57], v[170:171] op_sel_hi:[1,0]
	v_pk_mul_f32 v[54:55], v[54:55], v[170:171] op_sel_hi:[1,0]
	v_pk_mul_f32 v[52:53], v[52:53], v[170:171] op_sel_hi:[1,0]
	v_pk_mul_f32 v[50:51], v[50:51], v[170:171] op_sel_hi:[1,0]
	v_pk_mul_f32 v[48:49], v[48:49], v[170:171] op_sel_hi:[1,0]
	v_pk_mul_f32 v[46:47], v[46:47], v[170:171] op_sel_hi:[1,0]
	v_pk_mul_f32 v[44:45], v[44:45], v[170:171] op_sel_hi:[1,0]
	v_pk_mul_f32 v[42:43], v[42:43], v[170:171] op_sel_hi:[1,0]
	v_pk_mul_f32 v[40:41], v[40:41], v[170:171] op_sel_hi:[1,0]
	v_pk_mul_f32 v[38:39], v[38:39], v[170:171] op_sel_hi:[1,0]
	v_pk_mul_f32 v[36:37], v[36:37], v[170:171] op_sel_hi:[1,0]
	v_pk_mul_f32 v[34:35], v[34:35], v[170:171] op_sel_hi:[1,0]
	v_pk_mul_f32 v[32:33], v[32:33], v[170:171] op_sel_hi:[1,0]
	v_pk_mul_f32 v[30:31], v[30:31], v[170:171] op_sel_hi:[1,0]
	v_pk_mul_f32 v[28:29], v[28:29], v[170:171] op_sel_hi:[1,0]
	v_pk_mul_f32 v[26:27], v[26:27], v[170:171] op_sel_hi:[1,0]
	v_pk_mul_f32 v[24:25], v[24:25], v[170:171] op_sel_hi:[1,0]
	v_pk_mul_f32 v[22:23], v[22:23], v[170:171] op_sel_hi:[1,0]
	v_pk_mul_f32 v[20:21], v[20:21], v[170:171] op_sel_hi:[1,0]
	v_pk_mul_f32 v[18:19], v[18:19], v[170:171] op_sel_hi:[1,0]
	v_pk_mul_f32 v[16:17], v[16:17], v[170:171] op_sel_hi:[1,0]
	v_pk_mul_f32 v[14:15], v[14:15], v[170:171] op_sel_hi:[1,0]
	v_pk_mul_f32 v[12:13], v[12:13], v[170:171] op_sel_hi:[1,0]
	v_pk_mul_f32 v[10:11], v[10:11], v[170:171] op_sel_hi:[1,0]
	v_pk_mul_f32 v[8:9], v[8:9], v[170:171] op_sel_hi:[1,0]
	v_pk_mul_f32 v[6:7], v[6:7], v[170:171] op_sel_hi:[1,0]
	v_pk_mul_f32 v[4:5], v[4:5], v[170:171] op_sel_hi:[1,0]
	v_pk_mul_f32 v[2:3], v[2:3], v[170:171] op_sel_hi:[1,0]
	v_pk_mul_f32 v[0:1], v[0:1], v[170:171] op_sel_hi:[1,0]

; #define ATT_ISSUE(tilebase, bufbase) do { const unsigned char* _tb = (tilebase); asm volatile("" : "+s"(_tb)); _Pragma("unroll") for (int _i = 0; _i < 6; ++_i) { int _q = wave + 8 * _i; _q = _q > 44 ? 44 : _q; \
;         __builtin_amdgcn_global_load_lds((const unsigned*)(_tb + goff[_i]), (LAS unsigned*)((bufbase) + _q * 1024), 16, 0, 0); } } while (0)
; #define ATT_BAR() do { asm volatile("s_waitcnt vmcnt(0) lgkmcnt(0)" ::: "memory"); __builtin_amdgcn_s_barrier(); asm volatile("" ::: "memory"); } while (0)
; __device__ __forceinline__ void att_mfma(const Params& P, LAS unsigned char* lds, int wave) {
;     ...
;         for (int kt = 0; kt < ntile; ++kt) {
;             if (kt + 1 < ntile) ATT_ISSUE(kvb + (size_t)(kt + 1) * 327680, lds + bnext * BUF);
;             if (!roleA && kt >= 1 && kt - 1 <= my_last) att_pv(lds + bprev * BUF, vlane, pb, o);
;             if (kt <= my_last) att_qk_sm(lds + bcur * BUF, klane, qf, o, mrun, lrun, pb);
;             if (roleA && kt <= my_last) att_pv(lds + bcur * BUF, vlane, pb, o);
;             ATT_BAR();
;             bprev = bcur; bcur = bnext; bnext = bnext == 2 ? 0 : bnext + 1;
;         }
.LBB0_1024:
	s_add_i32 s4, s59, 1
	s_cmp_lg_u32 s59, 2
	s_waitcnt vmcnt(0) lgkmcnt(0)
	s_barrier
	s_cselect_b32 s61, s4, 0
	s_add_u32 s10, s10, s77
	s_addc_u32 s11, s11, s78
	s_cmp_eq_u32 s50, s60
	s_cbranch_scc1 .LBB0_1026
	s_mov_b32 s16, s60
	s_mov_b32 s17, s58
	s_mov_b32 s58, s59
	s_add_i32 s60, s16, 1
	s_cmp_ge_u32 s60, s50
	s_mov_b32 s59, s61
	s_cbranch_scc0 .LBB0_1015
	s_branch .LBB0_1016
